# UP GEMM: first two vmcnt waits of a tile that follows an epilogue allow the 16 epilogue stores to stay outstanding (store drain overlaps the first MFMA blocks)
# baseline (speedup 1.0000x reference)
; #define LAS __attribute__((address_space(3)))
; __global__ void __launch_bounds__(512, 2) fwd(Params P) {
;     extern __shared__ __attribute__((aligned(16))) unsigned char lds_raw[];
;     LAS unsigned char* lds = (LAS unsigned char*)lds_raw;
;     const int tid = threadIdx.x, lane = tid & 63, wave = __builtin_amdgcn_readfirstlane(tid >> 6);
;     const int G = gridDim.x, bx = blockIdx.x;
;     const int vcu = (G % 8 == 0) ? (bx % 8) * (G / 8) + bx / 8 : bx;
;     const int gw = vcu * 8 + wave, NGW = G * 8;
_Z3fwd6Params:
	s_mov_b32 s98, 0
	s_load_dword s3, s[0:1], 0xb0
	s_add_u32 s6, s0, 0xb0
	s_mov_b32 s84, s2
	v_and_b32_e32 v178, 0x3ff, v0
	s_addc_u32 s7, s1, 0
	s_waitcnt lgkmcnt(0)
	s_and_b32 s2, s3, 7
	v_readfirstlane_b32 s12, v178
	s_cmp_lg_u32 s2, 0
	s_mov_b32 s2, s84
	s_cbranch_scc1 .LBB0_2
	s_ashr_i32 s4, s84, 31
	s_lshr_b32 s4, s4, 29
	s_add_i32 s4, s84, s4
	s_and_b32 s5, s4, -8
	s_ashr_i32 s2, s3, 3
	s_sub_i32 s5, s84, s5
	s_mul_i32 s2, s2, s5
	s_ashr_i32 s4, s4, 3
	s_add_i32 s2, s2, s4

; #define PG8_STAGE(bufoff, gbase, voff) do { _Pragma("unroll") for (int _i = 0; _i < 2; ++_i) \
;         __builtin_amdgcn_global_load_lds((const unsigned*)((const char*)(gbase) + (voff)[_i]), (PG8_LAS unsigned*)(lds + (bufoff) + ldsw + _i * 8192), 16, 0, 0); } while (0)
; #define PG8_LDA(dst, b, h) do { _Pragma("unroll") for (int m = 0; m < 4; ++m) _Pragma("unroll") for (int k = 0; k < 2; ++k) dst[m][k] = *(const PG8_LAS bf16x8*)(lds + PG8_SA(b, h) + aoff + m * 2048 + k * 1024); } while (0)
; #define PG8_LDB(dst, b, h) do { _Pragma("unroll") for (int n = 0; n < 2; ++n) _Pragma("unroll") for (int k = 0; k < 2; ++k) dst[n][k] = *(const PG8_LAS bf16x8*)(lds + PG8_SB(b, h) + boff + n * 2048 + k * 1024); } while (0)
; #define PG8_MMA(ai, bj, At, Bt) do { __builtin_amdgcn_s_setprio(1); _Pragma("unroll") for (int m = 0; m < 4; ++m) _Pragma("unroll") for (int n = 0; n < 2; ++n) _Pragma("unroll") for (int k = 0; k < 2; ++k) \
;         acc[ai][bj][m][n] = __builtin_amdgcn_mfma_f32_16x16x32_bf16(Bt[n][k], At[m][k], acc[ai][bj][m][n], 0, 0, 0); __builtin_amdgcn_s_setprio(0); } while (0)
; #define PG8_WAIT_V(n) asm volatile("s_waitcnt vmcnt(" #n ")" ::: "memory")
; #define PG8_WAIT_L(n) asm volatile("s_waitcnt lgkmcnt(" #n ")" ::: "memory")
; #define PG8_BAR __builtin_amdgcn_s_barrier()
; #define PG8_SCHED __builtin_amdgcn_sched_barrier(0)
; template <class Epi, class Sched, bool ALIGN_EPI = false, bool SP2 = false>
; __device__ __forceinline__ void gemm_phase(PG8_LAS unsigned char* lds, const Gemm g, const Sched& S, const Epi& E) {
;     ...
;             PG8_LDB(B0, 0, 0); PG8_LDB(B1, 0, 1); PG8_SCHED; PG8_LDA(At, 0, 0); PG8_STAGE(PG8_SA(1, 1), a1 + hstep, voffA);
;             PG8_WAIT_V(8); PG8_WAIT_L(0); PG8_BAR; PG8_MMA(0, 0, At, B0); PG8_MMA(0, 1, At, B1); PG8_BAR; PG8_SCHED;
;             PG8_LDA(At, 0, 1); PG8_STAGE(PG8_SB(0, 0), b2, voffB); PG8_STAGE(PG8_SB(0, 1), b2 + hstep, voffB); PG8_STAGE(PG8_SA(0, 0), a2, voffA);
;             PG8_WAIT_V(8); PG8_WAIT_L(0); PG8_BAR; PG8_MMA(1, 0, At, B0); PG8_MMA(1, 1, At, B1); PG8_BAR; PG8_SCHED;
.LBB0_1294:
	ds_read_b128 v[154:157], v150
	ds_read_b128 v[158:161], v150 offset:1024
	ds_read_b128 v[162:165], v150 offset:2048
	ds_read_b128 v[168:171], v150 offset:3072
	ds_read_b128 v[172:175], v151
	ds_read_b128 v[182:185], v151 offset:1024
	ds_read_b128 v[186:189], v151 offset:2048
	ds_read_b128 v[190:193], v151 offset:3072
	s_add_u32 s30, s28, 0xfff80080
	s_addc_u32 s31, s29, -1
	s_cmp_eq_u32 s53, 28
	s_cselect_b32 s35, s21, s31
	s_cselect_b32 s34, s49, s30
	s_cselect_b32 s31, s19, s52
	s_cselect_b32 s30, s50, s51
	v_lshl_add_u64 v[146:147], s[28:29], 0, v[138:139]
	s_add_i32 m0, s40, 0xc000
	ds_read_b128 v[194:197], v152
	ds_read_b128 v[198:201], v152 offset:1024
	ds_read_b128 v[202:205], v152 offset:2048
	ds_read_b128 v[206:209], v152 offset:3072
	ds_read_b128 v[210:213], v152 offset:4096
	ds_read_b128 v[214:217], v152 offset:5120
	ds_read_b128 v[218:221], v152 offset:6144
	ds_read_b128 v[222:225], v152 offset:7168
	global_load_lds_dwordx4 v[146:147], off
	v_lshl_add_u64 v[146:147], s[28:29], 0, v[140:141]
	s_add_i32 m0, s40, 0xe000
	s_nop 0
	global_load_lds_dwordx4 v[146:147], off
	s_cmp_eq_u32 s98, 0
	s_cbranch_scc1 .Lup_w0_n
	s_waitcnt vmcnt(24)
	s_branch .Lup_w0_j
.Lup_w0_n:
	s_waitcnt vmcnt(8)
.Lup_w0_j:
	s_waitcnt lgkmcnt(0)
	s_barrier
	s_setprio 1
	s_waitcnt lgkmcnt(0)
	v_mfma_f32_16x16x32_bf16 v[124:127], v[154:157], v[194:197], v[124:127]
	v_mfma_f32_16x16x32_bf16 v[120:123], v[162:165], v[194:197], v[120:123]
	v_mfma_f32_16x16x32_bf16 v[112:115], v[154:157], v[202:205], v[112:115]
	v_mfma_f32_16x16x32_bf16 v[104:107], v[162:165], v[202:205], v[104:107]
	v_mfma_f32_16x16x32_bf16 v[96:99], v[154:157], v[210:213], v[96:99]
	v_mfma_f32_16x16x32_bf16 v[88:91], v[162:165], v[210:213], v[88:91]
	v_mfma_f32_16x16x32_bf16 v[80:83], v[154:157], v[218:221], v[80:83]
	v_mfma_f32_16x16x32_bf16 v[72:75], v[162:165], v[218:221], v[72:75]
	v_mfma_f32_16x16x32_bf16 v[124:127], v[158:161], v[198:201], v[124:127]
	v_mfma_f32_16x16x32_bf16 v[120:123], v[168:171], v[198:201], v[120:123]
	v_mfma_f32_16x16x32_bf16 v[112:115], v[158:161], v[206:209], v[112:115]
	v_mfma_f32_16x16x32_bf16 v[104:107], v[168:171], v[206:209], v[104:107]
	v_mfma_f32_16x16x32_bf16 v[96:99], v[158:161], v[214:217], v[96:99]
	v_mfma_f32_16x16x32_bf16 v[88:91], v[168:171], v[214:217], v[88:91]
	v_mfma_f32_16x16x32_bf16 v[80:83], v[158:161], v[222:225], v[80:83]
	v_mfma_f32_16x16x32_bf16 v[72:75], v[168:171], v[222:225], v[72:75]
	s_setprio 0
	s_setprio 1
	v_mfma_f32_16x16x32_bf16 v[116:119], v[172:175], v[194:197], v[116:119]
	v_mfma_f32_16x16x32_bf16 v[108:111], v[186:189], v[194:197], v[108:111]
	v_mfma_f32_16x16x32_bf16 v[100:103], v[172:175], v[202:205], v[100:103]
	v_mfma_f32_16x16x32_bf16 v[92:95], v[186:189], v[202:205], v[92:95]
	v_mfma_f32_16x16x32_bf16 v[84:87], v[172:175], v[210:213], v[84:87]
	v_mfma_f32_16x16x32_bf16 v[76:79], v[186:189], v[210:213], v[76:79]
	v_mfma_f32_16x16x32_bf16 v[68:71], v[172:175], v[218:221], v[68:71]
	v_mfma_f32_16x16x32_bf16 v[64:67], v[186:189], v[218:221], v[64:67]
	v_mfma_f32_16x16x32_bf16 v[116:119], v[182:185], v[198:201], v[116:119]
	v_mfma_f32_16x16x32_bf16 v[108:111], v[190:193], v[198:201], v[108:111]
	v_mfma_f32_16x16x32_bf16 v[100:103], v[182:185], v[206:209], v[100:103]
	v_mfma_f32_16x16x32_bf16 v[92:95], v[190:193], v[206:209], v[92:95]
	v_mfma_f32_16x16x32_bf16 v[84:87], v[182:185], v[214:217], v[84:87]
	v_mfma_f32_16x16x32_bf16 v[76:79], v[190:193], v[214:217], v[76:79]
	v_mfma_f32_16x16x32_bf16 v[68:71], v[182:185], v[222:225], v[68:71]
	v_mfma_f32_16x16x32_bf16 v[64:67], v[190:193], v[222:225], v[64:67]
	s_setprio 0
	s_barrier
	s_add_i32 s55, s47, s39
	v_lshl_add_u64 v[146:147], s[30:31], 0, v[132:133]
	s_mov_b32 m0, s55
	ds_read_b128 v[194:197], v152 offset:16384
	ds_read_b128 v[198:201], v152 offset:17408
	ds_read_b128 v[202:205], v152 offset:18432
	ds_read_b128 v[206:209], v152 offset:19456
	ds_read_b128 v[210:213], v152 offset:20480
	ds_read_b128 v[214:217], v152 offset:21504
	ds_read_b128 v[218:221], v152 offset:22528
	ds_read_b128 v[222:225], v152 offset:23552
	global_load_lds_dwordx4 v[146:147], off
	s_add_i32 m0, s55, 0x2000
	s_add_u32 s56, s30, 0x80000
	v_lshl_add_u64 v[176:177], s[30:31], 0, v[128:129]
	s_addc_u32 s57, s31, 0
	s_add_i32 s55, s48, s39
	global_load_lds_dwordx4 v[176:177], off
	v_lshl_add_u64 v[226:227], s[56:57], 0, v[132:133]
	s_mov_b32 m0, s55
	v_lshl_add_u64 v[228:229], s[34:35], 0, v[130:131]
	global_load_lds_dwordx4 v[226:227], off
	v_lshl_add_u64 v[226:227], s[56:57], 0, v[128:129]
	s_add_i32 m0, s55, 0x2000
	s_nop 0
	global_load_lds_dwordx4 v[226:227], off
	v_lshl_add_u64 v[226:227], s[34:35], 0, v[134:135]
	s_mov_b32 m0, s40
	s_nop 0
	global_load_lds_dwordx4 v[226:227], off
	s_mov_b32 m0, s41
	s_nop 0
	global_load_lds_dwordx4 v[228:229], off
	s_cmp_eq_u32 s98, 0
	s_cbranch_scc1 .Lup_w1_n
	s_waitcnt vmcnt(24)
	s_mov_b32 s98, 0
	s_branch .Lup_w1_j

; #define PG8_STAGE(bufoff, gbase, voff) do { _Pragma("unroll") for (int _i = 0; _i < 2; ++_i) \
;         __builtin_amdgcn_global_load_lds((const unsigned*)((const char*)(gbase) + (voff)[_i]), (PG8_LAS unsigned*)(lds + (bufoff) + ldsw + _i * 8192), 16, 0, 0); } while (0)
; #define PG8_LDA(dst, b, h) do { _Pragma("unroll") for (int m = 0; m < 4; ++m) _Pragma("unroll") for (int k = 0; k < 2; ++k) dst[m][k] = *(const PG8_LAS bf16x8*)(lds + PG8_SA(b, h) + aoff + m * 2048 + k * 1024); } while (0)
; #define PG8_LDB(dst, b, h) do { _Pragma("unroll") for (int n = 0; n < 2; ++n) _Pragma("unroll") for (int k = 0; k < 2; ++k) dst[n][k] = *(const PG8_LAS bf16x8*)(lds + PG8_SB(b, h) + boff + n * 2048 + k * 1024); } while (0)
; #define PG8_MMA(ai, bj, At, Bt) do { __builtin_amdgcn_s_setprio(1); _Pragma("unroll") for (int m = 0; m < 4; ++m) _Pragma("unroll") for (int n = 0; n < 2; ++n) _Pragma("unroll") for (int k = 0; k < 2; ++k) \
;         acc[ai][bj][m][n] = __builtin_amdgcn_mfma_f32_16x16x32_bf16(Bt[n][k], At[m][k], acc[ai][bj][m][n], 0, 0, 0); __builtin_amdgcn_s_setprio(0); } while (0)
; #define PG8_WAIT_V(n) asm volatile("s_waitcnt vmcnt(" #n ")" ::: "memory")
; #define PG8_WAIT_L(n) asm volatile("s_waitcnt lgkmcnt(" #n ")" ::: "memory")
; #define PG8_BAR __builtin_amdgcn_s_barrier()
; #define PG8_SCHED __builtin_amdgcn_sched_barrier(0)
; template <class Epi, class Sched, bool ALIGN_EPI = false, bool SP2 = false>
; __device__ __forceinline__ void gemm_phase(PG8_LAS unsigned char* lds, const Gemm g, const Sched& S, const Epi& E) {
;     ...
;             PG8_WAIT_V(8); PG8_WAIT_L(0); PG8_BAR; PG8_MMA(1, 0, At, B0); PG8_MMA(1, 1, At, B1); PG8_BAR; PG8_SCHED;
;             PG8_LDB(B0, 1, 0); PG8_LDB(B1, 1, 1); PG8_SCHED; PG8_LDA(At, 1, 0); PG8_STAGE(PG8_SA(0, 1), a2 + hstep, voffA);
;             PG8_WAIT_V(8); PG8_WAIT_L(0); PG8_BAR; PG8_MMA(0, 0, At, B0); PG8_MMA(0, 1, At, B1); PG8_BAR; PG8_SCHED;
.Lup_w1_j:
	s_waitcnt lgkmcnt(0)
	s_barrier
	s_setprio 1
	s_waitcnt lgkmcnt(0)
	v_mfma_f32_16x16x32_bf16 v[60:63], v[154:157], v[194:197], v[60:63]
	v_mfma_f32_16x16x32_bf16 v[56:59], v[162:165], v[194:197], v[56:59]
	v_mfma_f32_16x16x32_bf16 v[48:51], v[154:157], v[202:205], v[48:51]
	v_mfma_f32_16x16x32_bf16 v[40:43], v[162:165], v[202:205], v[40:43]
	v_mfma_f32_16x16x32_bf16 v[32:35], v[154:157], v[210:213], v[32:35]
	v_mfma_f32_16x16x32_bf16 v[24:27], v[162:165], v[210:213], v[24:27]
	v_mfma_f32_16x16x32_bf16 v[16:19], v[154:157], v[218:221], v[16:19]
	v_mfma_f32_16x16x32_bf16 v[8:11], v[162:165], v[218:221], v[8:11]
	v_mfma_f32_16x16x32_bf16 v[60:63], v[158:161], v[198:201], v[60:63]
	v_mfma_f32_16x16x32_bf16 v[56:59], v[168:171], v[198:201], v[56:59]
	v_mfma_f32_16x16x32_bf16 v[48:51], v[158:161], v[206:209], v[48:51]
	v_mfma_f32_16x16x32_bf16 v[40:43], v[168:171], v[206:209], v[40:43]
	v_mfma_f32_16x16x32_bf16 v[32:35], v[158:161], v[214:217], v[32:35]
	v_mfma_f32_16x16x32_bf16 v[24:27], v[168:171], v[214:217], v[24:27]
	v_mfma_f32_16x16x32_bf16 v[16:19], v[158:161], v[222:225], v[16:19]
	v_mfma_f32_16x16x32_bf16 v[8:11], v[168:171], v[222:225], v[8:11]
	s_setprio 0
	s_setprio 1
	v_mfma_f32_16x16x32_bf16 v[52:55], v[172:175], v[194:197], v[52:55]
	v_mfma_f32_16x16x32_bf16 v[44:47], v[186:189], v[194:197], v[44:47]
	v_mfma_f32_16x16x32_bf16 v[36:39], v[172:175], v[202:205], v[36:39]
	v_mfma_f32_16x16x32_bf16 v[28:31], v[186:189], v[202:205], v[28:31]
	v_mfma_f32_16x16x32_bf16 v[20:23], v[172:175], v[210:213], v[20:23]
	v_mfma_f32_16x16x32_bf16 v[12:15], v[186:189], v[210:213], v[12:15]
	v_mfma_f32_16x16x32_bf16 v[4:7], v[172:175], v[218:221], v[4:7]
	v_mfma_f32_16x16x32_bf16 v[0:3], v[186:189], v[218:221], v[0:3]
	v_mfma_f32_16x16x32_bf16 v[52:55], v[182:185], v[198:201], v[52:55]
	v_mfma_f32_16x16x32_bf16 v[44:47], v[190:193], v[198:201], v[44:47]
	v_mfma_f32_16x16x32_bf16 v[36:39], v[182:185], v[206:209], v[36:39]
	v_mfma_f32_16x16x32_bf16 v[28:31], v[190:193], v[206:209], v[28:31]
	v_mfma_f32_16x16x32_bf16 v[20:23], v[182:185], v[214:217], v[20:23]
	v_mfma_f32_16x16x32_bf16 v[12:15], v[190:193], v[214:217], v[12:15]
	v_mfma_f32_16x16x32_bf16 v[4:7], v[182:185], v[222:225], v[4:7]
	v_mfma_f32_16x16x32_bf16 v[0:3], v[190:193], v[222:225], v[0:3]
	s_setprio 0
	s_barrier
	s_add_i32 s55, 0, 0x18000
	v_add_u32_e32 v153, s55, v149
	s_add_i32 s56, 0, 0x1c000
	ds_read_b128 v[154:157], v153
	ds_read_b128 v[158:161], v153 offset:1024
	ds_read_b128 v[162:165], v153 offset:2048
	ds_read_b128 v[168:171], v153 offset:3072
	v_add_u32_e32 v153, s56, v149
	ds_read_b128 v[172:175], v153
	ds_read_b128 v[182:185], v153 offset:1024
	ds_read_b128 v[186:189], v153 offset:2048
	ds_read_b128 v[190:193], v153 offset:3072
	s_add_u32 s34, s34, 0x80000
	s_addc_u32 s35, s35, 0
	s_mov_b32 m0, s42
	v_lshl_add_u64 v[230:231], s[34:35], 0, v[134:135]
	ds_read_b128 v[194:197], v152 offset:32768
	ds_read_b128 v[198:201], v152 offset:33792
	ds_read_b128 v[202:205], v152 offset:34816
	ds_read_b128 v[206:209], v152 offset:35840
	ds_read_b128 v[210:213], v152 offset:36864
	ds_read_b128 v[214:217], v152 offset:37888
	ds_read_b128 v[218:221], v152 offset:38912
	ds_read_b128 v[222:225], v152 offset:39936
	global_load_lds_dwordx4 v[230:231], off
	v_lshl_add_u64 v[230:231], s[34:35], 0, v[130:131]
	s_mov_b32 m0, s43
	s_nop 0
	global_load_lds_dwordx4 v[230:231], off
	s_waitcnt vmcnt(8)
	s_waitcnt lgkmcnt(0)
	s_barrier
	s_setprio 1
	s_waitcnt lgkmcnt(0)
	v_mfma_f32_16x16x32_bf16 v[124:127], v[154:157], v[194:197], v[124:127]
	v_mfma_f32_16x16x32_bf16 v[120:123], v[162:165], v[194:197], v[120:123]
	v_mfma_f32_16x16x32_bf16 v[112:115], v[154:157], v[202:205], v[112:115]
	v_mfma_f32_16x16x32_bf16 v[104:107], v[162:165], v[202:205], v[104:107]
	v_mfma_f32_16x16x32_bf16 v[96:99], v[154:157], v[210:213], v[96:99]
	v_mfma_f32_16x16x32_bf16 v[88:91], v[162:165], v[210:213], v[88:91]
	v_mfma_f32_16x16x32_bf16 v[80:83], v[154:157], v[218:221], v[80:83]
	v_mfma_f32_16x16x32_bf16 v[72:75], v[162:165], v[218:221], v[72:75]
	v_mfma_f32_16x16x32_bf16 v[124:127], v[158:161], v[198:201], v[124:127]
	v_mfma_f32_16x16x32_bf16 v[120:123], v[168:171], v[198:201], v[120:123]
	v_mfma_f32_16x16x32_bf16 v[112:115], v[158:161], v[206:209], v[112:115]
	v_mfma_f32_16x16x32_bf16 v[104:107], v[168:171], v[206:209], v[104:107]
	v_mfma_f32_16x16x32_bf16 v[96:99], v[158:161], v[214:217], v[96:99]
	v_mfma_f32_16x16x32_bf16 v[88:91], v[168:171], v[214:217], v[88:91]
	v_mfma_f32_16x16x32_bf16 v[80:83], v[158:161], v[222:225], v[80:83]
	v_mfma_f32_16x16x32_bf16 v[72:75], v[168:171], v[222:225], v[72:75]
	s_setprio 0
	s_setprio 1
	v_mfma_f32_16x16x32_bf16 v[116:119], v[172:175], v[194:197], v[116:119]
	v_mfma_f32_16x16x32_bf16 v[108:111], v[186:189], v[194:197], v[108:111]
	v_mfma_f32_16x16x32_bf16 v[100:103], v[172:175], v[202:205], v[100:103]
	v_mfma_f32_16x16x32_bf16 v[92:95], v[186:189], v[202:205], v[92:95]
	v_mfma_f32_16x16x32_bf16 v[84:87], v[172:175], v[210:213], v[84:87]
	v_mfma_f32_16x16x32_bf16 v[76:79], v[186:189], v[210:213], v[76:79]
	v_mfma_f32_16x16x32_bf16 v[68:71], v[172:175], v[218:221], v[68:71]
	v_mfma_f32_16x16x32_bf16 v[64:67], v[186:189], v[218:221], v[64:67]
	v_mfma_f32_16x16x32_bf16 v[116:119], v[182:185], v[198:201], v[116:119]
	v_mfma_f32_16x16x32_bf16 v[108:111], v[190:193], v[198:201], v[108:111]
	v_mfma_f32_16x16x32_bf16 v[100:103], v[182:185], v[206:209], v[100:103]
	v_mfma_f32_16x16x32_bf16 v[92:95], v[190:193], v[206:209], v[92:95]
	v_mfma_f32_16x16x32_bf16 v[84:87], v[182:185], v[214:217], v[84:87]
	v_mfma_f32_16x16x32_bf16 v[76:79], v[190:193], v[214:217], v[76:79]
	v_mfma_f32_16x16x32_bf16 v[68:71], v[182:185], v[222:225], v[68:71]
	v_mfma_f32_16x16x32_bf16 v[64:67], v[190:193], v[222:225], v[64:67]
	s_setprio 0
	s_barrier
; #define PG8_STAGE(bufoff, gbase, voff) do { _Pragma("unroll") for (int _i = 0; _i < 2; ++_i) \
;         __builtin_amdgcn_global_load_lds((const unsigned*)((const char*)(gbase) + (voff)[_i]), (PG8_LAS unsigned*)(lds + (bufoff) + ldsw + _i * 8192), 16, 0, 0); } while (0)
; #define PG8_LDA(dst, b, h) do { _Pragma("unroll") for (int m = 0; m < 4; ++m) _Pragma("unroll") for (int k = 0; k < 2; ++k) dst[m][k] = *(const PG8_LAS bf16x8*)(lds + PG8_SA(b, h) + aoff + m * 2048 + k * 1024); } while (0)
; #define PG8_LDB(dst, b, h) do { _Pragma("unroll") for (int n = 0; n < 2; ++n) _Pragma("unroll") for (int k = 0; k < 2; ++k) dst[n][k] = *(const PG8_LAS bf16x8*)(lds + PG8_SB(b, h) + boff + n * 2048 + k * 1024); } while (0)
; #define PG8_MMA(ai, bj, At, Bt) do { __builtin_amdgcn_s_setprio(1); _Pragma("unroll") for (int m = 0; m < 4; ++m) _Pragma("unroll") for (int n = 0; n < 2; ++n) _Pragma("unroll") for (int k = 0; k < 2; ++k) \
;         acc[ai][bj][m][n] = __builtin_amdgcn_mfma_f32_16x16x32_bf16(Bt[n][k], At[m][k], acc[ai][bj][m][n], 0, 0, 0); __builtin_amdgcn_s_setprio(0); } while (0)
; #define PG8_BAR __builtin_amdgcn_s_barrier()
; template <class Epi, class Sched, bool ALIGN_EPI = false, bool SP2 = false>
; __device__ __forceinline__ void gemm_phase(PG8_LAS unsigned char* lds, const Gemm g, const Sched& S, const Epi& E) {
;     ...
;             PG8_LDB(B0, 1, 0); PG8_LDB(B1, 1, 1); PG8_SCHED; PG8_LDA(At, 1, 0); PG8_STAGE(PG8_SA(0, 1), a2 + hstep, voffA);
;             PG8_WAIT_V(8); PG8_WAIT_L(0); PG8_BAR; PG8_MMA(0, 0, At, B0); PG8_MMA(0, 1, At, B1); PG8_BAR; PG8_SCHED;
;             PG8_LDA(At, 1, 1); PG8_STAGE(PG8_SB(1, 0), b3, voffB); PG8_STAGE(PG8_SB(1, 1), b3 + hstep, voffB); PG8_STAGE(PG8_SA(1, 0), a3, voffA);
;             PG8_WAIT_V(8); PG8_WAIT_L(0); PG8_BAR; PG8_MMA(1, 0, At, B0); PG8_MMA(1, 1, At, B1); PG8_BAR; PG8_SCHED;
;     __device__ __forceinline__ void operator()(const pg8::f32x4 (&acc)[2][2][4][2], const pg8::Unit& u, int wr, int wc, int fr, int fq) const {
;     ...
;                     } else if constexpr (KIND == EK_UP) {
; #pragma unroll
;                         for (int j = 0; j < 8; ++j) { const float r = fmaxf(v[j], 0.f); v[j] = r * r; }
;                         { u32x4 w; w.x = pk2(v[0], v[1]); w.y = pk2(v[2], v[3]); w.z = pk2(v[4], v[5]); w.w = pk2(v[6], v[7]); __builtin_nontemporal_store(w, (u32x4*)(a.o0 + (size_t)row * FF + pn * 256 + cl)); }
	s_add_i32 s34, s55, s39
	v_lshl_add_u64 v[146:147], v[146:147], 0, s[14:15]
	s_mov_b32 m0, s34
	ds_read_b128 v[194:197], v152 offset:49152
	ds_read_b128 v[198:201], v152 offset:50176
	ds_read_b128 v[202:205], v152 offset:51200
	ds_read_b128 v[206:209], v152 offset:52224
	ds_read_b128 v[210:213], v152 offset:53248
	ds_read_b128 v[214:217], v152 offset:54272
	ds_read_b128 v[218:221], v152 offset:55296
	ds_read_b128 v[222:225], v152 offset:56320
	global_load_lds_dwordx4 v[146:147], off
	s_add_i32 m0, s34, 0x2000
	s_add_u32 s30, s30, 0x80080
	v_lshl_add_u64 v[146:147], v[176:177], 0, s[14:15]
	s_addc_u32 s31, s31, 0
	s_add_i32 s34, s56, s39
	global_load_lds_dwordx4 v[146:147], off
	v_lshl_add_u64 v[146:147], s[30:31], 0, v[132:133]
	s_mov_b32 m0, s34
	s_nop 0
	global_load_lds_dwordx4 v[146:147], off
	v_lshl_add_u64 v[146:147], s[30:31], 0, v[128:129]
	s_add_i32 m0, s34, 0x2000
	s_nop 0
	global_load_lds_dwordx4 v[146:147], off
	v_lshl_add_u64 v[146:147], v[226:227], 0, s[14:15]
	s_mov_b32 m0, s45
	s_nop 0
	global_load_lds_dwordx4 v[146:147], off
	v_lshl_add_u64 v[146:147], v[228:229], 0, s[14:15]
	s_mov_b32 m0, s46
	s_nop 0
	global_load_lds_dwordx4 v[146:147], off
	s_waitcnt vmcnt(8)
	s_waitcnt lgkmcnt(0)
	s_barrier
	s_setprio 1
	s_waitcnt lgkmcnt(0)
	v_mfma_f32_16x16x32_bf16 v[60:63], v[154:157], v[194:197], v[60:63]
	v_mfma_f32_16x16x32_bf16 v[56:59], v[162:165], v[194:197], v[56:59]
	v_mfma_f32_16x16x32_bf16 v[48:51], v[154:157], v[202:205], v[48:51]
	v_mfma_f32_16x16x32_bf16 v[40:43], v[162:165], v[202:205], v[40:43]
	v_mfma_f32_16x16x32_bf16 v[32:35], v[154:157], v[210:213], v[32:35]
	v_mfma_f32_16x16x32_bf16 v[24:27], v[162:165], v[210:213], v[24:27]
	v_mfma_f32_16x16x32_bf16 v[16:19], v[154:157], v[218:221], v[16:19]
	v_mfma_f32_16x16x32_bf16 v[8:11], v[162:165], v[218:221], v[8:11]
	v_mfma_f32_16x16x32_bf16 v[60:63], v[158:161], v[198:201], v[60:63]
	v_mfma_f32_16x16x32_bf16 v[56:59], v[168:171], v[198:201], v[56:59]
	v_mfma_f32_16x16x32_bf16 v[48:51], v[158:161], v[206:209], v[48:51]
	v_mfma_f32_16x16x32_bf16 v[40:43], v[168:171], v[206:209], v[40:43]
	v_mfma_f32_16x16x32_bf16 v[32:35], v[158:161], v[214:217], v[32:35]
	v_mfma_f32_16x16x32_bf16 v[24:27], v[168:171], v[214:217], v[24:27]
	v_mfma_f32_16x16x32_bf16 v[16:19], v[158:161], v[222:225], v[16:19]
	v_mfma_f32_16x16x32_bf16 v[8:11], v[168:171], v[222:225], v[8:11]
	s_setprio 0
	s_setprio 1
	v_mfma_f32_16x16x32_bf16 v[52:55], v[172:175], v[194:197], v[52:55]
	v_mfma_f32_16x16x32_bf16 v[44:47], v[186:189], v[194:197], v[44:47]
	v_mfma_f32_16x16x32_bf16 v[36:39], v[172:175], v[202:205], v[36:39]
	v_mfma_f32_16x16x32_bf16 v[28:31], v[186:189], v[202:205], v[28:31]
	v_mfma_f32_16x16x32_bf16 v[20:23], v[172:175], v[210:213], v[20:23]
	v_mfma_f32_16x16x32_bf16 v[12:15], v[186:189], v[210:213], v[12:15]
	v_mfma_f32_16x16x32_bf16 v[4:7], v[172:175], v[218:221], v[4:7]
	v_mfma_f32_16x16x32_bf16 v[0:3], v[186:189], v[218:221], v[0:3]
	v_mfma_f32_16x16x32_bf16 v[52:55], v[182:185], v[198:201], v[52:55]
	v_mfma_f32_16x16x32_bf16 v[44:47], v[190:193], v[198:201], v[44:47]
	v_mfma_f32_16x16x32_bf16 v[36:39], v[182:185], v[206:209], v[36:39]
	v_mfma_f32_16x16x32_bf16 v[28:31], v[190:193], v[206:209], v[28:31]
	v_mfma_f32_16x16x32_bf16 v[20:23], v[182:185], v[214:217], v[20:23]
	v_mfma_f32_16x16x32_bf16 v[12:15], v[190:193], v[214:217], v[12:15]
	v_mfma_f32_16x16x32_bf16 v[4:7], v[182:185], v[222:225], v[4:7]
	v_mfma_f32_16x16x32_bf16 v[0:3], v[190:193], v[222:225], v[0:3]
	s_setprio 0
	s_barrier
	s_add_i32 s53, s53, 2
	s_add_u32 s28, s28, 0x100
	s_addc_u32 s29, s29, 0
	s_add_u32 s51, s51, 0x100
	s_addc_u32 s52, s52, 0
	s_cmp_gt_u32 s53, 29
	s_cbranch_scc0 .LBB0_1294
	s_and_b64 vcc, exec, s[16:17]
	s_cbranch_vccz .LBB0_1297
	s_barrier
.LBB0_1297:
	v_lshl_add_u32 v146, s26, 8, v148
	v_max_f32_e32 v120, 0, v120
	v_max_f32_e32 v121, 0, v121
	s_lshl_b32 s26, s27, 8
	v_ashrrev_i32_e32 v147, 31, v146
	v_max_f32_e32 v124, 0, v124
	v_max_f32_e32 v125, 0, v125
	v_pk_mul_f32 v[156:157], v[120:121], v[120:121]
	s_ashr_i32 s27, s26, 31
	v_lshlrev_b64 v[154:155], 14, v[146:147]
	v_pk_mul_f32 v[124:125], v[124:125], v[124:125]
	v_max_f32_e32 v120, 0, v122
	v_max_f32_e32 v121, 0, v123
	v_max_f32_e32 v126, 0, v126
	v_max_f32_e32 v127, 0, v127
	v_pk_mul_f32 v[158:159], v[120:121], v[120:121]
	v_cvt_pk_bf16_f32 v120, v124, v125
	v_lshl_add_u64 v[124:125], s[12:13], 0, v[154:155]
	s_lshl_b64 s[26:27], s[26:27], 1
	v_pk_mul_f32 v[126:127], v[126:127], v[126:127]
	v_lshl_add_u64 v[124:125], v[124:125], 0, s[26:27]
	v_cvt_pk_bf16_f32 v121, v126, v127
	v_cvt_pk_bf16_f32 v122, v156, v157
	v_cvt_pk_bf16_f32 v123, v158, v159
	v_lshl_add_u64 v[124:125], v[124:125], 0, v[136:137]
	v_max_f32_e32 v108, 0, v108
	v_max_f32_e32 v109, 0, v109
	global_store_dwordx4 v[124:125], v[120:123], off nt
	s_nop 1
	v_pk_mul_f32 v[120:121], v[108:109], v[108:109]
	v_max_f32_e32 v116, 0, v116
	v_max_f32_e32 v117, 0, v117
	v_max_f32_e32 v118, 0, v118
	v_max_f32_e32 v119, 0, v119
	v_max_f32_e32 v108, 0, v110
	v_max_f32_e32 v109, 0, v111
	v_pk_mul_f32 v[116:117], v[116:117], v[116:117]
	v_pk_mul_f32 v[118:119], v[118:119], v[118:119]
	v_pk_mul_f32 v[122:123], v[108:109], v[108:109]
	v_cvt_pk_bf16_f32 v108, v116, v117
	v_cvt_pk_bf16_f32 v109, v118, v119
	v_cvt_pk_bf16_f32 v110, v120, v121
	v_cvt_pk_bf16_f32 v111, v122, v123
	global_store_dwordx4 v[124:125], v[108:111], off offset:256 nt
	s_nop 1
	v_or_b32_e32 v108, 16, v146
	v_ashrrev_i32_e32 v109, 31, v108
	v_max_f32_e32 v104, 0, v104
	v_max_f32_e32 v105, 0, v105
	v_lshlrev_b64 v[108:109], 14, v[108:109]
	v_max_f32_e32 v110, v112, v112
	v_max_f32_e32 v111, v113, v113
	v_max_f32_e32 v112, v114, v114
; __device__ __forceinline__ unsigned pk2(float lo, float hi) { return pg8::cvt_pk_bf16(lo, hi); }
;     __device__ __forceinline__ void operator()(const pg8::f32x4 (&acc)[2][2][4][2], const pg8::Unit& u, int wr, int wc, int fr, int fq) const {
;     ...
;                     } else if constexpr (KIND == EK_UP) {
; #pragma unroll
;                         for (int j = 0; j < 8; ++j) { const float r = fmaxf(v[j], 0.f); v[j] = r * r; }
;                         { u32x4 w; w.x = pk2(v[0], v[1]); w.y = pk2(v[2], v[3]); w.z = pk2(v[4], v[5]); w.w = pk2(v[6], v[7]); __builtin_nontemporal_store(w, (u32x4*)(a.o0 + (size_t)row * FF + pn * 256 + cl)); }
	v_max_f32_e32 v113, v115, v115
	v_pk_mul_f32 v[114:115], v[104:105], v[104:105]
	v_max_f32_e32 v110, 0, v110
	v_max_f32_e32 v111, 0, v111
	v_max_f32_e32 v112, 0, v112
	v_max_f32_e32 v113, 0, v113
	v_max_f32_e32 v104, 0, v106
	v_max_f32_e32 v105, 0, v107
	v_lshl_add_u64 v[108:109], s[12:13], 0, v[108:109]
	v_pk_mul_f32 v[110:111], v[110:111], v[110:111]
	v_pk_mul_f32 v[112:113], v[112:113], v[112:113]
	v_pk_mul_f32 v[116:117], v[104:105], v[104:105]
	v_lshl_add_u64 v[108:109], v[108:109], 0, s[26:27]
	v_cvt_pk_bf16_f32 v104, v110, v111
	v_cvt_pk_bf16_f32 v105, v112, v113
	v_cvt_pk_bf16_f32 v106, v114, v115
	v_cvt_pk_bf16_f32 v107, v116, v117
	v_lshl_add_u64 v[108:109], v[108:109], 0, v[136:137]
	v_max_f32_e32 v92, 0, v92
	v_max_f32_e32 v93, 0, v93
	global_store_dwordx4 v[108:109], v[104:107], off nt
	s_nop 1
	v_pk_mul_f32 v[104:105], v[92:93], v[92:93]
	v_max_f32_e32 v100, 0, v100
	v_max_f32_e32 v101, 0, v101
	v_max_f32_e32 v102, 0, v102
	v_max_f32_e32 v103, 0, v103
	v_max_f32_e32 v92, 0, v94
	v_max_f32_e32 v93, 0, v95
	v_pk_mul_f32 v[100:101], v[100:101], v[100:101]
	v_pk_mul_f32 v[102:103], v[102:103], v[102:103]
	v_pk_mul_f32 v[106:107], v[92:93], v[92:93]
	v_cvt_pk_bf16_f32 v92, v100, v101
	v_cvt_pk_bf16_f32 v93, v102, v103
	v_cvt_pk_bf16_f32 v94, v104, v105
	v_cvt_pk_bf16_f32 v95, v106, v107
	global_store_dwordx4 v[108:109], v[92:95], off offset:256 nt
	s_nop 1
	v_or_b32_e32 v92, 32, v146
	v_ashrrev_i32_e32 v93, 31, v92
	v_max_f32_e32 v88, 0, v88
	v_max_f32_e32 v89, 0, v89
	v_lshlrev_b64 v[92:93], 14, v[92:93]
	v_max_f32_e32 v94, v96, v96
	v_max_f32_e32 v95, v97, v97
	v_max_f32_e32 v96, v98, v98
	v_max_f32_e32 v97, v99, v99
	v_pk_mul_f32 v[98:99], v[88:89], v[88:89]
	v_max_f32_e32 v94, 0, v94
	v_max_f32_e32 v95, 0, v95
	v_max_f32_e32 v96, 0, v96
	v_max_f32_e32 v97, 0, v97
	v_max_f32_e32 v88, 0, v90
	v_max_f32_e32 v89, 0, v91
	v_lshl_add_u64 v[92:93], s[12:13], 0, v[92:93]
	v_pk_mul_f32 v[94:95], v[94:95], v[94:95]
	v_pk_mul_f32 v[96:97], v[96:97], v[96:97]
	v_pk_mul_f32 v[100:101], v[88:89], v[88:89]
	v_lshl_add_u64 v[92:93], v[92:93], 0, s[26:27]
	v_cvt_pk_bf16_f32 v88, v94, v95
	v_cvt_pk_bf16_f32 v89, v96, v97
	v_cvt_pk_bf16_f32 v90, v98, v99
	v_cvt_pk_bf16_f32 v91, v100, v101
	v_lshl_add_u64 v[92:93], v[92:93], 0, v[136:137]
	v_max_f32_e32 v76, 0, v76
	v_max_f32_e32 v77, 0, v77
	global_store_dwordx4 v[92:93], v[88:91], off nt
	s_nop 1
	v_pk_mul_f32 v[88:89], v[76:77], v[76:77]
	v_max_f32_e32 v84, 0, v84
	v_max_f32_e32 v85, 0, v85
	v_max_f32_e32 v86, 0, v86
	v_max_f32_e32 v87, 0, v87
	v_max_f32_e32 v76, 0, v78
	v_max_f32_e32 v77, 0, v79
	v_pk_mul_f32 v[84:85], v[84:85], v[84:85]
	v_pk_mul_f32 v[86:87], v[86:87], v[86:87]
	v_pk_mul_f32 v[90:91], v[76:77], v[76:77]
	v_cvt_pk_bf16_f32 v76, v84, v85
	v_cvt_pk_bf16_f32 v77, v86, v87
	v_cvt_pk_bf16_f32 v78, v88, v89
	v_cvt_pk_bf16_f32 v79, v90, v91
	global_store_dwordx4 v[92:93], v[76:79], off offset:256 nt
	s_nop 1
	v_or_b32_e32 v76, 48, v146
	v_ashrrev_i32_e32 v77, 31, v76
	v_max_f32_e32 v72, 0, v72
	v_max_f32_e32 v73, 0, v73
	v_lshlrev_b64 v[76:77], 14, v[76:77]
	v_max_f32_e32 v78, v80, v80
	v_max_f32_e32 v79, v81, v81
	v_max_f32_e32 v80, v82, v82
	v_max_f32_e32 v81, v83, v83
	v_pk_mul_f32 v[82:83], v[72:73], v[72:73]
	v_max_f32_e32 v78, 0, v78
	v_max_f32_e32 v79, 0, v79
	v_max_f32_e32 v80, 0, v80
	v_max_f32_e32 v81, 0, v81
	v_max_f32_e32 v72, 0, v74
	v_max_f32_e32 v73, 0, v75
	v_lshl_add_u64 v[76:77], s[12:13], 0, v[76:77]
	v_pk_mul_f32 v[78:79], v[78:79], v[78:79]
	v_pk_mul_f32 v[80:81], v[80:81], v[80:81]
	v_pk_mul_f32 v[84:85], v[72:73], v[72:73]
	v_lshl_add_u64 v[76:77], v[76:77], 0, s[26:27]
	v_cvt_pk_bf16_f32 v72, v78, v79
	v_cvt_pk_bf16_f32 v73, v80, v81
	v_cvt_pk_bf16_f32 v74, v82, v83
	v_cvt_pk_bf16_f32 v75, v84, v85
	v_lshl_add_u64 v[76:77], v[76:77], 0, v[136:137]
	v_max_f32_e32 v64, 0, v64
	v_max_f32_e32 v65, 0, v65
	global_store_dwordx4 v[76:77], v[72:75], off nt
	s_nop 1
	v_pk_mul_f32 v[72:73], v[64:65], v[64:65]
	v_max_f32_e32 v68, 0, v68
	v_max_f32_e32 v69, 0, v69
	v_max_f32_e32 v70, 0, v70
	v_max_f32_e32 v71, 0, v71
	v_max_f32_e32 v64, 0, v66
	v_max_f32_e32 v65, 0, v67
	v_pk_mul_f32 v[68:69], v[68:69], v[68:69]
	v_pk_mul_f32 v[70:71], v[70:71], v[70:71]
	v_pk_mul_f32 v[74:75], v[64:65], v[64:65]
	v_cvt_pk_bf16_f32 v64, v68, v69
	v_cvt_pk_bf16_f32 v65, v70, v71
	v_cvt_pk_bf16_f32 v66, v72, v73
	v_cvt_pk_bf16_f32 v67, v74, v75
	global_store_dwordx4 v[76:77], v[64:67], off offset:256 nt
	s_nop 1
	v_add_u32_e32 v64, 0x80, v146
	v_max_f32_e32 v56, 0, v56
	v_max_f32_e32 v57, 0, v57
	v_ashrrev_i32_e32 v65, 31, v64
	v_max_f32_e32 v60, 0, v60
	v_max_f32_e32 v61, 0, v61
	v_pk_mul_f32 v[66:67], v[56:57], v[56:57]
	v_lshlrev_b64 v[64:65], 14, v[64:65]
	v_pk_mul_f32 v[60:61], v[60:61], v[60:61]
	v_max_f32_e32 v56, 0, v58
	v_max_f32_e32 v57, 0, v59
	v_max_f32_e32 v62, 0, v62
	v_max_f32_e32 v63, 0, v63
	v_pk_mul_f32 v[68:69], v[56:57], v[56:57]
	v_cvt_pk_bf16_f32 v56, v60, v61
	v_lshl_add_u64 v[60:61], s[12:13], 0, v[64:65]
	v_pk_mul_f32 v[62:63], v[62:63], v[62:63]
	v_lshl_add_u64 v[60:61], v[60:61], 0, s[26:27]
	v_cvt_pk_bf16_f32 v57, v62, v63
	v_cvt_pk_bf16_f32 v58, v66, v67
	v_cvt_pk_bf16_f32 v59, v68, v69
	v_lshl_add_u64 v[60:61], v[60:61], 0, v[136:137]
	v_max_f32_e32 v44, 0, v44
	v_max_f32_e32 v45, 0, v45
; #define PG8_BAR __builtin_amdgcn_s_barrier()
; __device__ __forceinline__ unsigned pk2(float lo, float hi) { return pg8::cvt_pk_bf16(lo, hi); }
; template <class Epi, class Sched, bool ALIGN_EPI = false, bool SP2 = false>
; __device__ __forceinline__ void gemm_phase(PG8_LAS unsigned char* lds, const Gemm g, const Sched& S, const Epi& E) {
;     ...
;         if (!has_next) break;
; #pragma unroll
;         for (int a = 0; a < 2; ++a)
; #pragma unroll
;             for (int b = 0; b < 2; ++b)
; #pragma unroll
;                 for (int m = 0; m < 4; ++m)
; #pragma unroll
;                     for (int n = 0; n < 2; ++n) acc[a][b][m][n] = (f32x4){0.f, 0.f, 0.f, 0.f};
;         cur = nxt; cA = nA; cB = nB; ++ui;
;         if constexpr (ALIGN_EPI) { if (wr == 1) PG8_BAR; }
;     }
;     __device__ __forceinline__ void operator()(const pg8::f32x4 (&acc)[2][2][4][2], const pg8::Unit& u, int wr, int wc, int fr, int fq) const {
;     ...
;                     } else if constexpr (KIND == EK_UP) {
; #pragma unroll
;                         for (int j = 0; j < 8; ++j) { const float r = fmaxf(v[j], 0.f); v[j] = r * r; }
;                         { u32x4 w; w.x = pk2(v[0], v[1]); w.y = pk2(v[2], v[3]); w.z = pk2(v[4], v[5]); w.w = pk2(v[6], v[7]); __builtin_nontemporal_store(w, (u32x4*)(a.o0 + (size_t)row * FF + pn * 256 + cl)); }
	global_store_dwordx4 v[60:61], v[56:59], off nt
	s_nop 1
	v_pk_mul_f32 v[56:57], v[44:45], v[44:45]
	v_max_f32_e32 v52, 0, v52
	v_max_f32_e32 v53, 0, v53
	v_max_f32_e32 v54, 0, v54
	v_max_f32_e32 v55, 0, v55
	v_max_f32_e32 v44, 0, v46
	v_max_f32_e32 v45, 0, v47
	v_pk_mul_f32 v[52:53], v[52:53], v[52:53]
	v_pk_mul_f32 v[54:55], v[54:55], v[54:55]
	v_pk_mul_f32 v[58:59], v[44:45], v[44:45]
	v_cvt_pk_bf16_f32 v44, v52, v53
	v_cvt_pk_bf16_f32 v45, v54, v55
	v_cvt_pk_bf16_f32 v46, v56, v57
	v_cvt_pk_bf16_f32 v47, v58, v59
	global_store_dwordx4 v[60:61], v[44:47], off offset:256 nt
	s_nop 1
	v_add_u32_e32 v44, 0x90, v146
	v_ashrrev_i32_e32 v45, 31, v44
	v_max_f32_e32 v40, 0, v40
	v_max_f32_e32 v41, 0, v41
	v_lshlrev_b64 v[44:45], 14, v[44:45]
	v_max_f32_e32 v46, v48, v48
	v_max_f32_e32 v47, v49, v49
	v_max_f32_e32 v48, v50, v50
	v_max_f32_e32 v49, v51, v51
	v_pk_mul_f32 v[50:51], v[40:41], v[40:41]
	v_max_f32_e32 v46, 0, v46
	v_max_f32_e32 v47, 0, v47
	v_max_f32_e32 v48, 0, v48
	v_max_f32_e32 v49, 0, v49
	v_max_f32_e32 v40, 0, v42
	v_max_f32_e32 v41, 0, v43
	v_lshl_add_u64 v[44:45], s[12:13], 0, v[44:45]
	v_pk_mul_f32 v[46:47], v[46:47], v[46:47]
	v_pk_mul_f32 v[48:49], v[48:49], v[48:49]
	v_pk_mul_f32 v[52:53], v[40:41], v[40:41]
	v_lshl_add_u64 v[44:45], v[44:45], 0, s[26:27]
	v_cvt_pk_bf16_f32 v40, v46, v47
	v_cvt_pk_bf16_f32 v41, v48, v49
	v_cvt_pk_bf16_f32 v42, v50, v51
	v_cvt_pk_bf16_f32 v43, v52, v53
	v_lshl_add_u64 v[44:45], v[44:45], 0, v[136:137]
	v_max_f32_e32 v28, 0, v28
	v_max_f32_e32 v29, 0, v29
	global_store_dwordx4 v[44:45], v[40:43], off nt
	s_nop 1
	v_pk_mul_f32 v[40:41], v[28:29], v[28:29]
	v_max_f32_e32 v36, 0, v36
	v_max_f32_e32 v37, 0, v37
	v_max_f32_e32 v38, 0, v38
	v_max_f32_e32 v39, 0, v39
	v_max_f32_e32 v28, 0, v30
	v_max_f32_e32 v29, 0, v31
	v_pk_mul_f32 v[36:37], v[36:37], v[36:37]
	v_pk_mul_f32 v[38:39], v[38:39], v[38:39]
	v_pk_mul_f32 v[42:43], v[28:29], v[28:29]
	v_cvt_pk_bf16_f32 v28, v36, v37
	v_cvt_pk_bf16_f32 v29, v38, v39
	v_cvt_pk_bf16_f32 v30, v40, v41
	v_cvt_pk_bf16_f32 v31, v42, v43
	global_store_dwordx4 v[44:45], v[28:31], off offset:256 nt
	s_nop 1
	v_add_u32_e32 v28, 0xa0, v146
	v_ashrrev_i32_e32 v29, 31, v28
	v_max_f32_e32 v24, 0, v24
	v_max_f32_e32 v25, 0, v25
	v_lshlrev_b64 v[28:29], 14, v[28:29]
	v_max_f32_e32 v30, v32, v32
	v_max_f32_e32 v31, v33, v33
	v_max_f32_e32 v32, v34, v34
	v_max_f32_e32 v33, v35, v35
	v_pk_mul_f32 v[34:35], v[24:25], v[24:25]
	v_max_f32_e32 v30, 0, v30
	v_max_f32_e32 v31, 0, v31
	v_max_f32_e32 v32, 0, v32
	v_max_f32_e32 v33, 0, v33
	v_max_f32_e32 v24, 0, v26
	v_max_f32_e32 v25, 0, v27
	v_lshl_add_u64 v[28:29], s[12:13], 0, v[28:29]
	v_pk_mul_f32 v[30:31], v[30:31], v[30:31]
	v_pk_mul_f32 v[32:33], v[32:33], v[32:33]
	v_pk_mul_f32 v[36:37], v[24:25], v[24:25]
	v_lshl_add_u64 v[28:29], v[28:29], 0, s[26:27]
	v_cvt_pk_bf16_f32 v24, v30, v31
	v_cvt_pk_bf16_f32 v25, v32, v33
	v_cvt_pk_bf16_f32 v26, v34, v35
	v_cvt_pk_bf16_f32 v27, v36, v37
	v_lshl_add_u64 v[28:29], v[28:29], 0, v[136:137]
	v_max_f32_e32 v12, 0, v12
	v_max_f32_e32 v13, 0, v13
	global_store_dwordx4 v[28:29], v[24:27], off nt
	s_nop 1
	v_pk_mul_f32 v[24:25], v[12:13], v[12:13]
	v_max_f32_e32 v20, 0, v20
	v_max_f32_e32 v21, 0, v21
	v_max_f32_e32 v22, 0, v22
	v_max_f32_e32 v23, 0, v23
	v_max_f32_e32 v12, 0, v14
	v_max_f32_e32 v13, 0, v15
	v_pk_mul_f32 v[20:21], v[20:21], v[20:21]
	v_pk_mul_f32 v[22:23], v[22:23], v[22:23]
	v_pk_mul_f32 v[26:27], v[12:13], v[12:13]
	v_cvt_pk_bf16_f32 v12, v20, v21
	v_cvt_pk_bf16_f32 v13, v22, v23
	v_cvt_pk_bf16_f32 v14, v24, v25
	v_cvt_pk_bf16_f32 v15, v26, v27
	global_store_dwordx4 v[28:29], v[12:15], off offset:256 nt
	s_nop 1
	v_add_u32_e32 v12, 0xb0, v146
	v_ashrrev_i32_e32 v13, 31, v12
	v_max_f32_e32 v8, 0, v8
	v_max_f32_e32 v9, 0, v9
	v_lshlrev_b64 v[12:13], 14, v[12:13]
	v_max_f32_e32 v14, v16, v16
	v_max_f32_e32 v15, v17, v17
	v_max_f32_e32 v16, v18, v18
	v_max_f32_e32 v17, v19, v19
	v_pk_mul_f32 v[18:19], v[8:9], v[8:9]
	v_max_f32_e32 v14, 0, v14
	v_max_f32_e32 v15, 0, v15
	v_max_f32_e32 v16, 0, v16
	v_max_f32_e32 v17, 0, v17
	v_max_f32_e32 v8, 0, v10
	v_max_f32_e32 v9, 0, v11
	v_lshl_add_u64 v[12:13], s[12:13], 0, v[12:13]
	v_pk_mul_f32 v[14:15], v[14:15], v[14:15]
	v_pk_mul_f32 v[16:17], v[16:17], v[16:17]
	v_pk_mul_f32 v[20:21], v[8:9], v[8:9]
	v_lshl_add_u64 v[12:13], v[12:13], 0, s[26:27]
	v_cvt_pk_bf16_f32 v8, v14, v15
	v_cvt_pk_bf16_f32 v9, v16, v17
	v_cvt_pk_bf16_f32 v10, v18, v19
	v_cvt_pk_bf16_f32 v11, v20, v21
	v_lshl_add_u64 v[12:13], v[12:13], 0, v[136:137]
	v_max_f32_e32 v0, 0, v0
	v_max_f32_e32 v1, 0, v1
	global_store_dwordx4 v[12:13], v[8:11], off nt
	s_nop 1
	v_pk_mul_f32 v[8:9], v[0:1], v[0:1]
	v_max_f32_e32 v4, 0, v4
	v_max_f32_e32 v5, 0, v5
	v_max_f32_e32 v6, 0, v6
	v_max_f32_e32 v7, 0, v7
	v_max_f32_e32 v0, 0, v2
	v_max_f32_e32 v1, 0, v3
	v_pk_mul_f32 v[4:5], v[4:5], v[4:5]
	v_pk_mul_f32 v[6:7], v[6:7], v[6:7]
	v_pk_mul_f32 v[10:11], v[0:1], v[0:1]
	v_cvt_pk_bf16_f32 v0, v4, v5
	v_cvt_pk_bf16_f32 v1, v6, v7
	v_cvt_pk_bf16_f32 v2, v8, v9
	v_cvt_pk_bf16_f32 v3, v10, v11
	s_andn2_b64 vcc, exec, s[8:9]
	s_mov_b64 s[8:9], -1
	global_store_dwordx4 v[12:13], v[0:3], off offset:256 nt
	s_mov_b32 s98, 1
	s_cbranch_vccnz .LBB0_1286
	s_andn2_b64 vcc, exec, s[10:11]
	s_cbranch_vccnz .LBB0_1285
	s_barrier
	s_branch .LBB0_1285

; __global__ void __launch_bounds__(512, 2) fwd(Params P) {
	.amdhsa_kernel _Z3fwd6Params
		.amdhsa_group_segment_fixed_size 0
		.amdhsa_private_segment_fixed_size 0
		.amdhsa_kernarg_size 432
		.amdhsa_user_sgpr_count 2
		.amdhsa_user_sgpr_dispatch_ptr 0
		.amdhsa_user_sgpr_queue_ptr 0
		.amdhsa_user_sgpr_kernarg_segment_ptr 1
		.amdhsa_user_sgpr_dispatch_id 0
		.amdhsa_user_sgpr_kernarg_preload_length 0
		.amdhsa_user_sgpr_kernarg_preload_offset 0
		.amdhsa_user_sgpr_private_segment_size 0
		.amdhsa_uses_dynamic_stack 0
		.amdhsa_enable_private_segment 0
		.amdhsa_system_sgpr_workgroup_id_x 1
		.amdhsa_system_sgpr_workgroup_id_y 0
		.amdhsa_system_sgpr_workgroup_id_z 0
		.amdhsa_system_sgpr_workgroup_info 0
		.amdhsa_system_vgpr_workitem_id 2
		.amdhsa_next_free_vgpr 247
		.amdhsa_next_free_sgpr 102
		.amdhsa_accum_offset 248
		.amdhsa_reserve_vcc 1
		.amdhsa_float_round_mode_32 0
		.amdhsa_float_round_mode_16_64 0
		.amdhsa_float_denorm_mode_32 3
		.amdhsa_float_denorm_mode_16_64 3
		.amdhsa_dx10_clamp 1
		.amdhsa_ieee_mode 1
		.amdhsa_fp16_overflow 0
		.amdhsa_tg_split 0
		.amdhsa_exception_fp_ieee_invalid_op 0
		.amdhsa_exception_fp_denorm_src 0
		.amdhsa_exception_fp_ieee_div_zero 0
		.amdhsa_exception_fp_ieee_overflow 0
		.amdhsa_exception_fp_ieee_underflow 0
		.amdhsa_exception_fp_ieee_inexact 0
		.amdhsa_exception_int_div_zero 0
	.end_amdhsa_kernel
